# v24 plus: mid q-up rope epilogue loop also touches its cos/sin block before the row loop
# baseline (speedup 1.0000x reference)
.LBB0_1145:
	s_or_b64 exec, exec, s[2:3]
	s_ashr_i32 s6, s34, 6
	s_cmp_gt_i32 s22, 7
	s_mov_b64 s[2:3], -1
	s_waitcnt lgkmcnt(0)
	s_barrier
	s_cbranch_scc0 .LBB0_1149
	s_and_b32 s2, s38, 0x1f80
	v_add_u32_e32 v1, s2, v132
	v_lshlrev_b32_e32 v4, 5, v1
	v_ashrrev_i32_e32 v5, 31, v4
	v_lshlrev_b64 v[4:5], 2, v[4:5]
	v_lshl_add_u64 v[6:7], v[134:135], 0, v[4:5]
	global_load_dwordx2 v[2:3], v[138:139], off
	v_lshl_add_u64 v[8:9], v[136:137], 0, v[4:5]
	v_and_b32_e32 v222, 63, v208
	v_mov_b32_e32 v223, 0
	v_lshlrev_b32_e32 v222, 6, v222
	v_lshl_add_u64 v[224:225], v[6:7], 0, v[222:223]
	v_lshl_add_u64 v[226:227], v[8:9], 0, v[222:223]
	global_load_dword v228, v[224:225], off
	global_load_dword v229, v[226:227], off
	global_load_dwordx2 v[4:5], v[6:7], off
	s_nop 0
	global_load_dwordx2 v[6:7], v[8:9], off
	v_cmp_lt_i32_e32 vcc, v216, v217
	s_lshl_b32 s3, s6, 3
	s_lshl_b32 s7, s31, 1
	v_cndmask_b32_e32 v8, v215, v216, vcc
	s_add_i32 s7, s7, s3
	v_lshlrev_b32_e32 v10, 2, v8
	v_add_u32_e32 v8, s7, v161
	s_mul_i32 s3, s34, 24
	v_subrev_u32_e32 v11, s3, v8
	v_mad_i64_i32 v[8:9], s[8:9], v1, s25, 0
	s_mov_b32 s3, 0x300000
	v_mad_i64_i32 v[8:9], s[8:9], v11, s3, v[8:9]
	s_mov_b32 s2, 0
	v_lshl_add_u64 v[8:9], v[140:141], 0, v[8:9]
	v_mov_b32_e32 v11, v133
